# K/Q epilogue: 4-way partial-sum add done with one v_pk_add on the ds_read result instead of 3 v_mov + v_pk_add (48 fewer VALU per K/Q tile per wave)
# speedup vs baseline: 1.0095x; 1.0039x over previous
.LBB0_745:
	s_or_b64 exec, exec, s[64:65]
	v_ashrrev_i32_e32 v219, 31, v218
	v_lshl_add_u64 v[202:203], v[218:219], 2, s[10:11]
	global_load_dword v200, v[202:203], off sc1
	global_load_dword v249, v[202:203], off offset:64 sc1
	global_load_dword v248, v[202:203], off offset:128 sc1
	global_load_dword v247, v[202:203], off offset:192 sc1
	global_load_dword v246, v[202:203], off offset:512 sc1
	global_load_dword v245, v[202:203], off offset:576 sc1
	global_load_dword v241, v[202:203], off offset:640 sc1
	global_load_dword v219, v[202:203], off offset:704 sc1
	v_mul_f32_e32 v202, v125, v125
	v_mul_f32_e32 v203, v127, v127
	v_fmac_f32_e32 v202, v124, v124
	v_fmac_f32_e32 v203, v126, v126
	v_add_f32_e32 v202, v202, v203
	v_mul_f32_e32 v203, v121, v121
	v_fmac_f32_e32 v203, v120, v120
	v_add_f32_e32 v202, v202, v203
	v_mul_f32_e32 v203, v123, v123
	v_fmac_f32_e32 v203, v122, v122
	v_add_f32_e32 v202, v203, v202
	v_mov_b32_e32 v203, v202
	s_nop 1
	v_permlane16_swap_b32_e32 v202, v203
	v_add_f32_e32 v203, v202, v203
	v_lshlrev_b32_e32 v250, 5, v240
	v_mov_b32_e32 v204, v203
	s_nop 1
	v_permlane32_swap_b32_e32 v203, v204
	v_add_u32_e32 v202, s79, v250
	s_and_saveexec_b64 s[60:61], s[8:9]
	v_add_f32_e32 v203, v203, v204
	ds_write_b32 v202, v203
	s_or_b64 exec, exec, s[60:61]
	v_mul_f32_e32 v203, v105, v105
	v_mul_f32_e32 v204, v107, v107
	v_fmac_f32_e32 v203, v104, v104
	v_fmac_f32_e32 v204, v106, v106
	v_add_f32_e32 v203, v203, v204
	v_mul_f32_e32 v204, v97, v97
	v_fmac_f32_e32 v204, v96, v96
	v_add_f32_e32 v203, v203, v204
	v_mul_f32_e32 v204, v99, v99
	v_fmac_f32_e32 v204, v98, v98
	v_add_f32_e32 v203, v204, v203
	v_mov_b32_e32 v204, v203
	s_nop 1
	v_permlane16_swap_b32_e32 v203, v204
	v_add_f32_e32 v203, v203, v204
	v_mov_b32_e32 v204, v203
	s_nop 1
	v_permlane32_swap_b32_e32 v203, v204
	s_and_saveexec_b64 s[60:61], s[8:9]
	v_add_f32_e32 v203, v203, v204
	ds_write_b32 v202, v203 offset:16
	s_or_b64 exec, exec, s[60:61]
	v_mul_f32_e32 v203, v117, v117
	v_mul_f32_e32 v204, v119, v119
	v_fmac_f32_e32 v203, v116, v116
	v_fmac_f32_e32 v204, v118, v118
	v_add_f32_e32 v203, v203, v204
	v_mul_f32_e32 v204, v113, v113
	v_fmac_f32_e32 v204, v112, v112
	v_add_f32_e32 v203, v203, v204
	v_mul_f32_e32 v204, v115, v115
	v_fmac_f32_e32 v204, v114, v114
	v_add_f32_e32 v203, v204, v203
	v_mov_b32_e32 v204, v203
	s_nop 1
	v_permlane16_swap_b32_e32 v203, v204
	v_add_f32_e32 v203, v203, v204
	v_mov_b32_e32 v204, v203
	s_nop 1
	v_permlane32_swap_b32_e32 v203, v204
	s_and_saveexec_b64 s[60:61], s[8:9]
	v_add_f32_e32 v203, v203, v204
	ds_write_b32 v202, v203 offset:512
	s_or_b64 exec, exec, s[60:61]
	v_mul_f32_e32 v203, v89, v89
	v_mul_f32_e32 v204, v91, v91
	v_fmac_f32_e32 v203, v88, v88
	v_fmac_f32_e32 v204, v90, v90
	v_add_f32_e32 v203, v203, v204
	v_mul_f32_e32 v204, v85, v85
	v_fmac_f32_e32 v204, v84, v84
	v_add_f32_e32 v203, v203, v204
	v_mul_f32_e32 v204, v87, v87
	v_fmac_f32_e32 v204, v86, v86
	v_add_f32_e32 v203, v204, v203
	v_mov_b32_e32 v204, v203
	s_nop 1
	v_permlane16_swap_b32_e32 v203, v204
	v_add_f32_e32 v203, v203, v204
	v_mov_b32_e32 v204, v203
	s_nop 1
	v_permlane32_swap_b32_e32 v203, v204
	s_and_saveexec_b64 s[60:61], s[8:9]
	v_add_f32_e32 v203, v203, v204
	ds_write_b32 v202, v203 offset:528
	s_or_b64 exec, exec, s[60:61]
	v_mul_f32_e32 v203, v109, v109
	v_mul_f32_e32 v204, v111, v111
	v_fmac_f32_e32 v203, v108, v108
	v_fmac_f32_e32 v204, v110, v110
	v_add_f32_e32 v203, v203, v204
	v_mul_f32_e32 v204, v101, v101
	v_fmac_f32_e32 v204, v100, v100
	v_add_f32_e32 v203, v203, v204
	v_mul_f32_e32 v204, v103, v103
	v_fmac_f32_e32 v204, v102, v102
	v_add_f32_e32 v203, v204, v203
	v_mov_b32_e32 v204, v203
	s_nop 1
	v_permlane16_swap_b32_e32 v203, v204
	v_add_f32_e32 v203, v203, v204
	v_mov_b32_e32 v204, v203
	s_nop 1
	v_permlane32_swap_b32_e32 v203, v204
	s_and_saveexec_b64 s[60:61], s[8:9]
	v_add_f32_e32 v203, v203, v204
	ds_write_b32 v202, v203 offset:1024
	s_or_b64 exec, exec, s[60:61]
	v_mul_f32_e32 v203, v77, v77
	v_mul_f32_e32 v204, v79, v79
	v_fmac_f32_e32 v203, v76, v76
	v_fmac_f32_e32 v204, v78, v78
	v_add_f32_e32 v203, v203, v204
	v_mul_f32_e32 v204, v73, v73
	v_fmac_f32_e32 v204, v72, v72
	v_add_f32_e32 v203, v203, v204
	v_mul_f32_e32 v204, v75, v75
	v_fmac_f32_e32 v204, v74, v74
	v_add_f32_e32 v203, v204, v203
	v_mov_b32_e32 v204, v203
	s_nop 1
	v_permlane16_swap_b32_e32 v203, v204
	v_add_f32_e32 v203, v203, v204
	v_mov_b32_e32 v204, v203
	s_nop 1
	v_permlane32_swap_b32_e32 v203, v204
	s_and_saveexec_b64 s[60:61], s[8:9]
	v_add_f32_e32 v203, v203, v204
	ds_write_b32 v202, v203 offset:1040
	s_or_b64 exec, exec, s[60:61]
	v_mul_f32_e32 v203, v93, v93
	v_mul_f32_e32 v204, v95, v95
	v_fmac_f32_e32 v203, v92, v92
	v_fmac_f32_e32 v204, v94, v94
	v_add_f32_e32 v203, v203, v204
	v_mul_f32_e32 v204, v81, v81
	v_fmac_f32_e32 v204, v80, v80
	v_add_f32_e32 v203, v203, v204
	v_mul_f32_e32 v204, v83, v83
	v_fmac_f32_e32 v204, v82, v82
	v_add_f32_e32 v203, v204, v203
	v_mov_b32_e32 v204, v203
	s_nop 1
	v_permlane16_swap_b32_e32 v203, v204
	v_add_f32_e32 v203, v203, v204
	v_mov_b32_e32 v204, v203
	s_nop 1
	v_permlane32_swap_b32_e32 v203, v204
	s_and_saveexec_b64 s[60:61], s[8:9]
	v_add_f32_e32 v203, v203, v204
	ds_write_b32 v202, v203 offset:1536
	s_or_b64 exec, exec, s[60:61]
	v_mul_f32_e32 v203, v69, v69
	v_mul_f32_e32 v204, v71, v71
	v_fmac_f32_e32 v203, v68, v68
	v_fmac_f32_e32 v204, v70, v70
	v_add_f32_e32 v203, v203, v204
	v_mul_f32_e32 v204, v65, v65
	v_fmac_f32_e32 v204, v64, v64
	v_add_f32_e32 v203, v203, v204
	v_mul_f32_e32 v204, v67, v67
	v_fmac_f32_e32 v204, v66, v66
	v_add_f32_e32 v203, v204, v203
	v_mov_b32_e32 v204, v203
	s_nop 1
	v_permlane16_swap_b32_e32 v203, v204
	v_add_f32_e32 v203, v203, v204
	v_mov_b32_e32 v204, v203
	s_nop 1
	v_permlane32_swap_b32_e32 v203, v204
	s_and_saveexec_b64 s[60:61], s[8:9]
	v_add_f32_e32 v203, v203, v204
	ds_write_b32 v202, v203 offset:1552
	s_or_b64 exec, exec, s[60:61]
	v_mul_f32_e32 v203, v61, v61
	v_mul_f32_e32 v204, v63, v63
	v_fmac_f32_e32 v203, v60, v60
	v_fmac_f32_e32 v204, v62, v62
	v_add_f32_e32 v203, v203, v204
	v_mul_f32_e32 v204, v57, v57
	v_fmac_f32_e32 v204, v56, v56
	v_add_f32_e32 v203, v203, v204
	v_mul_f32_e32 v204, v59, v59
	v_fmac_f32_e32 v204, v58, v58
	v_add_f32_e32 v203, v204, v203
	v_mov_b32_e32 v204, v203
	s_nop 1
	v_permlane16_swap_b32_e32 v203, v204
	v_add_f32_e32 v203, v203, v204
	v_mov_b32_e32 v204, v203
	s_nop 1
	v_permlane32_swap_b32_e32 v203, v204
	s_and_saveexec_b64 s[60:61], s[8:9]
	v_add_f32_e32 v203, v203, v204
	ds_write_b32 v202, v203 offset:4096
	s_or_b64 exec, exec, s[60:61]
	v_mul_f32_e32 v203, v53, v53
	v_mul_f32_e32 v204, v55, v55
	v_fmac_f32_e32 v203, v52, v52
	v_fmac_f32_e32 v204, v54, v54
	v_add_f32_e32 v203, v203, v204
	v_mul_f32_e32 v204, v45, v45
	v_fmac_f32_e32 v204, v44, v44
	v_add_f32_e32 v203, v203, v204
	v_mul_f32_e32 v204, v47, v47
	v_fmac_f32_e32 v204, v46, v46
	v_add_f32_e32 v203, v204, v203
	v_mov_b32_e32 v204, v203
	s_nop 1
	v_permlane16_swap_b32_e32 v203, v204
	v_add_f32_e32 v203, v203, v204
	v_mov_b32_e32 v204, v203
	s_nop 1
	v_permlane32_swap_b32_e32 v203, v204
	s_and_saveexec_b64 s[60:61], s[8:9]
	v_add_f32_e32 v203, v203, v204
	ds_write_b32 v202, v203 offset:4112
	s_or_b64 exec, exec, s[60:61]
	v_mul_f32_e32 v203, v49, v49
	v_mul_f32_e32 v204, v51, v51
	v_fmac_f32_e32 v203, v48, v48
	v_fmac_f32_e32 v204, v50, v50
	v_add_f32_e32 v203, v203, v204
	v_mul_f32_e32 v204, v41, v41
	v_fmac_f32_e32 v204, v40, v40
	v_add_f32_e32 v203, v203, v204
	v_mul_f32_e32 v204, v43, v43
	v_fmac_f32_e32 v204, v42, v42
	v_add_f32_e32 v203, v204, v203
	v_mov_b32_e32 v204, v203
	s_nop 1
	v_permlane16_swap_b32_e32 v203, v204
	v_add_f32_e32 v203, v203, v204
	v_mov_b32_e32 v204, v203
	s_nop 1
	v_permlane32_swap_b32_e32 v203, v204
	s_and_saveexec_b64 s[60:61], s[8:9]
	v_add_f32_e32 v203, v203, v204
	ds_write_b32 v202, v203 offset:4608
	s_or_b64 exec, exec, s[60:61]
	v_mul_f32_e32 v203, v37, v37
	v_mul_f32_e32 v204, v39, v39
	v_fmac_f32_e32 v203, v36, v36
	v_fmac_f32_e32 v204, v38, v38
	v_add_f32_e32 v203, v203, v204
	v_mul_f32_e32 v204, v29, v29
	v_fmac_f32_e32 v204, v28, v28
	v_add_f32_e32 v203, v203, v204
	v_mul_f32_e32 v204, v31, v31
	v_fmac_f32_e32 v204, v30, v30
	v_add_f32_e32 v203, v204, v203
	v_mov_b32_e32 v204, v203
	s_nop 1
	v_permlane16_swap_b32_e32 v203, v204
	v_add_f32_e32 v203, v203, v204
	v_mov_b32_e32 v204, v203
	s_nop 1
	v_permlane32_swap_b32_e32 v203, v204
	s_and_saveexec_b64 s[60:61], s[8:9]
	v_add_f32_e32 v203, v203, v204
	ds_write_b32 v202, v203 offset:4624
	s_or_b64 exec, exec, s[60:61]
	v_mul_f32_e32 v203, v33, v33
	v_mul_f32_e32 v204, v35, v35
	v_fmac_f32_e32 v203, v32, v32
	v_fmac_f32_e32 v204, v34, v34
	v_add_f32_e32 v203, v203, v204
	v_mul_f32_e32 v204, v25, v25
	v_fmac_f32_e32 v204, v24, v24
	v_add_f32_e32 v203, v203, v204
	v_mul_f32_e32 v204, v27, v27
	v_fmac_f32_e32 v204, v26, v26
	v_add_f32_e32 v203, v204, v203
	v_mov_b32_e32 v204, v203
	s_nop 1
	v_permlane16_swap_b32_e32 v203, v204
	v_add_f32_e32 v203, v203, v204
	v_mov_b32_e32 v204, v203
	s_nop 1
	v_permlane32_swap_b32_e32 v203, v204
	s_and_saveexec_b64 s[60:61], s[8:9]
	v_add_f32_e32 v203, v203, v204
	ds_write_b32 v202, v203 offset:5120
	s_or_b64 exec, exec, s[60:61]
	v_mul_f32_e32 v203, v21, v21
	v_mul_f32_e32 v204, v23, v23
	v_fmac_f32_e32 v203, v20, v20
	v_fmac_f32_e32 v204, v22, v22
	v_add_f32_e32 v203, v203, v204
	v_mul_f32_e32 v204, v13, v13
	v_fmac_f32_e32 v204, v12, v12
	v_add_f32_e32 v203, v203, v204
	v_mul_f32_e32 v204, v15, v15
	v_fmac_f32_e32 v204, v14, v14
	v_add_f32_e32 v203, v204, v203
	v_mov_b32_e32 v204, v203
	s_nop 1
	v_permlane16_swap_b32_e32 v203, v204
	v_add_f32_e32 v203, v203, v204
	v_mov_b32_e32 v204, v203
	s_nop 1
	v_permlane32_swap_b32_e32 v203, v204
	s_and_saveexec_b64 s[60:61], s[8:9]
	v_add_f32_e32 v203, v203, v204
	ds_write_b32 v202, v203 offset:5136
	s_or_b64 exec, exec, s[60:61]
	v_mul_f32_e32 v203, v17, v17
	v_mul_f32_e32 v204, v19, v19
	v_fmac_f32_e32 v203, v16, v16
	v_fmac_f32_e32 v204, v18, v18
	v_add_f32_e32 v203, v203, v204
	v_mul_f32_e32 v204, v9, v9
	v_fmac_f32_e32 v204, v8, v8
	v_add_f32_e32 v203, v203, v204
	v_mul_f32_e32 v204, v11, v11
	v_fmac_f32_e32 v204, v10, v10
	v_add_f32_e32 v203, v204, v203
	v_mov_b32_e32 v204, v203
	s_nop 1
	v_permlane16_swap_b32_e32 v203, v204
	v_add_f32_e32 v203, v203, v204
	v_mov_b32_e32 v204, v203
	s_nop 1
	v_permlane32_swap_b32_e32 v203, v204
	s_and_saveexec_b64 s[60:61], s[8:9]
	v_add_f32_e32 v203, v203, v204
	ds_write_b32 v202, v203 offset:5632
	s_or_b64 exec, exec, s[60:61]
	v_mul_f32_e32 v203, v5, v5
	v_mul_f32_e32 v204, v7, v7
	v_fmac_f32_e32 v203, v4, v4
	v_fmac_f32_e32 v204, v6, v6
	v_add_f32_e32 v203, v203, v204
	v_mul_f32_e32 v204, v1, v1
	v_fmac_f32_e32 v204, v0, v0
	v_add_f32_e32 v203, v203, v204
	v_mul_f32_e32 v204, v3, v3
	v_fmac_f32_e32 v204, v2, v2
	v_add_f32_e32 v203, v204, v203
	v_mov_b32_e32 v204, v203
	s_nop 1
	v_permlane16_swap_b32_e32 v203, v204
	v_add_f32_e32 v203, v203, v204
	v_mov_b32_e32 v204, v203
	s_nop 1
	v_permlane32_swap_b32_e32 v203, v204
	s_and_saveexec_b64 s[60:61], s[8:9]
	v_add_f32_e32 v203, v203, v204
	ds_write_b32 v202, v203 offset:5648
	s_or_b64 exec, exec, s[60:61]
	s_and_b64 s[60:61], s[62:63], exec
	s_cselect_b32 s60, s92, 0xc00
	s_lshr_b32 s61, s50, 1
	s_add_i32 s50, s50, -6
	s_lshr_b32 s64, s50, 2
	s_and_b64 s[50:51], s[62:63], exec
	s_cselect_b32 s61, s61, s64
	s_add_i32 s64, s39, 0xfffffa00
	v_add_u32_e32 v202, s80, v239
	v_mov_b32_e32 v203, s78
	s_and_b64 s[50:51], s[62:63], exec
	v_cndmask_b32_e64 v222, v202, v203, s[8:9]
	v_or_b32_e32 v202, 4, v202
	v_mov_b32_e32 v203, s81
	v_cndmask_b32_e64 v220, v202, v203, s[8:9]
	s_cselect_b32 s8, 0, 0x600
	s_cselect_b32 s50, s39, s64
	s_add_u32 s51, s82, s8
	s_addc_u32 s64, s83, 0
	s_lshl_b32 s8, s61, 7
	s_ashr_i32 s9, s8, 31
	s_lshl_b64 s[8:9], s[8:9], 2
	s_add_u32 s8, s51, s8
	s_addc_u32 s9, s64, s9
	v_ashrrev_i32_e32 v223, 31, v222
	v_ashrrev_i32_e32 v221, 31, v220
	s_waitcnt lgkmcnt(0)
	s_barrier
	s_waitcnt vmcnt(0)
	v_fmamk_f32 v204, v200, 0x3a800000, v238
	v_add_u32_e32 v200, 0x20000, v250
	ds_read_b128 v[200:203], v200
	v_mul_f32_e32 v251, 0x358637bd, v204
	v_mov_b32_e32 v205, 0x3e0293ee
	v_cndmask_b32_e64 v244, v205, 1.0, s[62:63]
	v_mad_i64_i32 v[204:205], s[8:9], s60, v218, 0
	s_waitcnt lgkmcnt(0)
	v_pk_add_f32 v[200:201], v[200:201], v[202:203]
	s_ashr_i32 s51, s50, 31
	v_add_f32_e32 v200, v200, v201
	v_fmamk_f32 v200, v200, 0x3c000000, v251
	v_rsq_f32_e32 v200, v200
	s_lshl_b64 s[8:9], s[50:51], 1
	s_add_u32 s8, s48, s8
	s_addc_u32 s9, s49, s9
	v_mul_f32_e32 v200, v244, v200
	v_pk_mul_f32 v[202:203], v[124:125], v[200:201] op_sel_hi:[1,0]
	v_pk_mul_f32 v[226:227], v[126:127], v[200:201] op_sel_hi:[1,0]
	v_pk_mul_f32 v[252:253], v[120:121], v[200:201] op_sel_hi:[1,0]
	v_pk_mul_f32 v[200:201], v[122:123], v[200:201] op_sel_hi:[1,0]
	v_lshl_add_u64 v[230:231], v[204:205], 1, s[8:9]
	v_lshl_add_u64 v[224:225], v[222:223], 1, v[230:231]
	v_pk_mul_f32 v[228:229], v[154:155], v[226:227]
	v_pk_mul_f32 v[202:203], v[152:153], v[202:203]
	v_pk_mul_f32 v[226:227], v[158:159], v[200:201]
	v_pk_mul_f32 v[200:201], v[156:157], v[252:253]
	s_and_saveexec_b64 s[50:51], vcc
	s_xor_b64 s[50:51], exec, s[50:51]
	s_cbranch_execz .LBB0_779
	v_cvt_pk_bf16_f32 v202, v202, v203
	v_cvt_pk_bf16_f32 v203, v228, v229
	v_cvt_pk_bf16_f32 v204, v200, v201
	v_cvt_pk_bf16_f32 v205, v226, v227
	global_store_dwordx4 v[224:225], v[202:205], off

.LBB0_781:
	s_or_b64 exec, exec, s[50:51]
	v_add_u32_e32 v200, 0x20010, v250
	ds_read_b128 v[200:203], v200
	s_waitcnt lgkmcnt(0)
	v_pk_add_f32 v[200:201], v[200:201], v[202:203]
	s_nop 0
	v_add_f32_e32 v200, v200, v201
	v_fmac_f32_e32 v251, 0x3c000000, v200
	v_rsq_f32_e32 v200, v251
	s_nop 0
	v_mul_f32_e32 v200, v244, v200
	v_pk_mul_f32 v[202:203], v[104:105], v[200:201] op_sel_hi:[1,0]
	v_pk_mul_f32 v[226:227], v[106:107], v[200:201] op_sel_hi:[1,0]
	v_pk_mul_f32 v[230:231], v[96:97], v[200:201] op_sel_hi:[1,0]
	v_pk_mul_f32 v[200:201], v[98:99], v[200:201] op_sel_hi:[1,0]
	v_pk_mul_f32 v[228:229], v[154:155], v[226:227]
	v_pk_mul_f32 v[202:203], v[152:153], v[202:203]
	v_pk_mul_f32 v[226:227], v[158:159], v[200:201]
	v_pk_mul_f32 v[200:201], v[156:157], v[230:231]
	s_and_saveexec_b64 s[50:51], vcc
	s_xor_b64 s[50:51], exec, s[50:51]
	s_cbranch_execz .LBB0_783
	v_cvt_pk_bf16_f32 v192, v202, v203
	v_cvt_pk_bf16_f32 v193, v228, v229
	v_cvt_pk_bf16_f32 v194, v200, v201
	v_cvt_pk_bf16_f32 v195, v226, v227
	global_store_dwordx4 v[224:225], v[192:195], off offset:256

.LBB0_785:
	s_or_b64 exec, exec, s[50:51]
	v_add_u32_e32 v196, 16, v240
	v_lshlrev_b32_e32 v225, 5, v196
	v_add_u32_e32 v192, 0x20000, v225
	ds_read_b128 v[192:195], v192
	v_fmamk_f32 v197, v249, 0x3a800000, v238
	v_mul_f32_e32 v224, 0x358637bd, v197
	v_add_u32_e32 v198, s41, v196
	s_waitcnt lgkmcnt(0)
	v_pk_add_f32 v[192:193], v[192:193], v[194:195]
	s_nop 0
	v_add_f32_e32 v192, v192, v193
	v_fmamk_f32 v192, v192, 0x3c000000, v224
	v_rsq_f32_e32 v194, v192
	v_mad_i64_i32 v[192:193], s[50:51], s60, v198, 0
	v_lshl_add_u64 v[200:201], v[192:193], 1, s[8:9]
	v_mul_f32_e32 v192, v244, v194
	v_pk_mul_f32 v[196:197], v[118:119], v[192:193] op_sel_hi:[1,0]
	v_pk_mul_f32 v[194:195], v[116:117], v[192:193] op_sel_hi:[1,0]
	v_pk_mul_f32 v[202:203], v[154:155], v[196:197]
	v_pk_mul_f32 v[196:197], v[112:113], v[192:193] op_sel_hi:[1,0]
	v_pk_mul_f32 v[192:193], v[114:115], v[192:193] op_sel_hi:[1,0]
	v_lshl_add_u64 v[198:199], v[222:223], 1, v[200:201]
	v_pk_mul_f32 v[194:195], v[152:153], v[194:195]
	v_pk_mul_f32 v[204:205], v[158:159], v[192:193]
	v_pk_mul_f32 v[192:193], v[156:157], v[196:197]
	s_and_saveexec_b64 s[50:51], vcc
	s_xor_b64 s[50:51], exec, s[50:51]
	s_cbranch_execz .LBB0_787
	v_cvt_pk_bf16_f32 v194, v194, v195
	v_cvt_pk_bf16_f32 v195, v202, v203
	v_cvt_pk_bf16_f32 v196, v192, v193
	v_cvt_pk_bf16_f32 v197, v204, v205
	global_store_dwordx4 v[198:199], v[194:197], off

.LBB0_789:
	s_or_b64 exec, exec, s[50:51]
	v_add_u32_e32 v192, 0x20010, v225
	ds_read_b128 v[192:195], v192
	s_waitcnt lgkmcnt(0)
	v_pk_add_f32 v[192:193], v[192:193], v[194:195]
	s_nop 0
	v_add_f32_e32 v192, v192, v193
	v_fmac_f32_e32 v224, 0x3c000000, v192
	v_rsq_f32_e32 v192, v224
	s_nop 0
	v_mul_f32_e32 v192, v244, v192
	v_pk_mul_f32 v[194:195], v[88:89], v[192:193] op_sel_hi:[1,0]
	v_pk_mul_f32 v[200:201], v[90:91], v[192:193] op_sel_hi:[1,0]
	v_pk_mul_f32 v[204:205], v[84:85], v[192:193] op_sel_hi:[1,0]
	v_pk_mul_f32 v[192:193], v[86:87], v[192:193] op_sel_hi:[1,0]
	v_pk_mul_f32 v[202:203], v[154:155], v[200:201]
	v_pk_mul_f32 v[194:195], v[152:153], v[194:195]
	v_pk_mul_f32 v[200:201], v[158:159], v[192:193]
	v_pk_mul_f32 v[192:193], v[156:157], v[204:205]
	s_and_saveexec_b64 s[50:51], vcc
	s_xor_b64 s[50:51], exec, s[50:51]
	s_cbranch_execz .LBB0_791
	v_cvt_pk_bf16_f32 v184, v194, v195
	v_cvt_pk_bf16_f32 v185, v202, v203
	v_cvt_pk_bf16_f32 v186, v192, v193
	v_cvt_pk_bf16_f32 v187, v200, v201
	global_store_dwordx4 v[198:199], v[184:187], off offset:256

.LBB0_793:
	s_or_b64 exec, exec, s[50:51]
	v_add_u32_e32 v188, 32, v240
	v_lshlrev_b32_e32 v199, 5, v188
	v_add_u32_e32 v184, 0x20000, v199
	ds_read_b128 v[184:187], v184
	v_fmamk_f32 v189, v248, 0x3a800000, v238
	v_mul_f32_e32 v198, 0x358637bd, v189
	v_add_u32_e32 v190, s41, v188
	s_waitcnt lgkmcnt(0)
	v_pk_add_f32 v[184:185], v[184:185], v[186:187]
	s_nop 0
	v_add_f32_e32 v184, v184, v185
	v_fmamk_f32 v184, v184, 0x3c000000, v198
	v_rsq_f32_e32 v186, v184
	v_mad_i64_i32 v[184:185], s[50:51], s60, v190, 0
	v_lshl_add_u64 v[192:193], v[184:185], 1, s[8:9]
	v_mul_f32_e32 v184, v244, v186
	v_pk_mul_f32 v[188:189], v[110:111], v[184:185] op_sel_hi:[1,0]
	v_pk_mul_f32 v[186:187], v[108:109], v[184:185] op_sel_hi:[1,0]
	v_pk_mul_f32 v[194:195], v[154:155], v[188:189]
	v_pk_mul_f32 v[188:189], v[100:101], v[184:185] op_sel_hi:[1,0]
	v_pk_mul_f32 v[184:185], v[102:103], v[184:185] op_sel_hi:[1,0]
	v_lshl_add_u64 v[190:191], v[222:223], 1, v[192:193]
	v_pk_mul_f32 v[186:187], v[152:153], v[186:187]
	v_pk_mul_f32 v[196:197], v[158:159], v[184:185]
	v_pk_mul_f32 v[184:185], v[156:157], v[188:189]
	s_and_saveexec_b64 s[50:51], vcc
	s_xor_b64 s[50:51], exec, s[50:51]
	s_cbranch_execz .LBB0_795
	v_cvt_pk_bf16_f32 v186, v186, v187
	v_cvt_pk_bf16_f32 v187, v194, v195
	v_cvt_pk_bf16_f32 v188, v184, v185
	v_cvt_pk_bf16_f32 v189, v196, v197
	global_store_dwordx4 v[190:191], v[186:189], off

.LBB0_797:
	s_or_b64 exec, exec, s[50:51]
	v_add_u32_e32 v184, 0x20010, v199
	ds_read_b128 v[184:187], v184
	s_waitcnt lgkmcnt(0)
	v_pk_add_f32 v[184:185], v[184:185], v[186:187]
	s_nop 0
	v_add_f32_e32 v184, v184, v185
	v_fmac_f32_e32 v198, 0x3c000000, v184
	v_rsq_f32_e32 v184, v198
	s_nop 0
	v_mul_f32_e32 v184, v244, v184
	v_pk_mul_f32 v[186:187], v[76:77], v[184:185] op_sel_hi:[1,0]
	v_pk_mul_f32 v[192:193], v[78:79], v[184:185] op_sel_hi:[1,0]
	v_pk_mul_f32 v[196:197], v[72:73], v[184:185] op_sel_hi:[1,0]
	v_pk_mul_f32 v[184:185], v[74:75], v[184:185] op_sel_hi:[1,0]
	v_pk_mul_f32 v[194:195], v[154:155], v[192:193]
	v_pk_mul_f32 v[186:187], v[152:153], v[186:187]
	v_pk_mul_f32 v[192:193], v[158:159], v[184:185]
	v_pk_mul_f32 v[184:185], v[156:157], v[196:197]
	s_and_saveexec_b64 s[50:51], vcc
	s_xor_b64 s[50:51], exec, s[50:51]
	s_cbranch_execz .LBB0_799
	v_cvt_pk_bf16_f32 v176, v186, v187
	v_cvt_pk_bf16_f32 v177, v194, v195
	v_cvt_pk_bf16_f32 v178, v184, v185
	v_cvt_pk_bf16_f32 v179, v192, v193
	global_store_dwordx4 v[190:191], v[176:179], off offset:256

.LBB0_801:
	s_or_b64 exec, exec, s[50:51]
	v_add_u32_e32 v180, 48, v240
	v_lshlrev_b32_e32 v191, 5, v180
	v_add_u32_e32 v176, 0x20000, v191
	ds_read_b128 v[176:179], v176
	v_fmamk_f32 v181, v247, 0x3a800000, v238
	v_mul_f32_e32 v190, 0x358637bd, v181
	v_add_u32_e32 v182, s41, v180
	s_waitcnt lgkmcnt(0)
	v_pk_add_f32 v[176:177], v[176:177], v[178:179]
	s_nop 0
	v_add_f32_e32 v176, v176, v177
	v_fmamk_f32 v176, v176, 0x3c000000, v190
	v_rsq_f32_e32 v178, v176
	v_mad_i64_i32 v[176:177], s[50:51], s60, v182, 0
	v_lshl_add_u64 v[184:185], v[176:177], 1, s[8:9]
	v_mul_f32_e32 v176, v244, v178
	v_pk_mul_f32 v[180:181], v[94:95], v[176:177] op_sel_hi:[1,0]
	v_pk_mul_f32 v[178:179], v[92:93], v[176:177] op_sel_hi:[1,0]
	v_pk_mul_f32 v[186:187], v[154:155], v[180:181]
	v_pk_mul_f32 v[180:181], v[80:81], v[176:177] op_sel_hi:[1,0]
	v_pk_mul_f32 v[176:177], v[82:83], v[176:177] op_sel_hi:[1,0]
	v_lshl_add_u64 v[182:183], v[222:223], 1, v[184:185]
	v_pk_mul_f32 v[178:179], v[152:153], v[178:179]
	v_pk_mul_f32 v[188:189], v[158:159], v[176:177]
	v_pk_mul_f32 v[176:177], v[156:157], v[180:181]
	s_and_saveexec_b64 s[50:51], vcc
	s_xor_b64 s[50:51], exec, s[50:51]
	s_cbranch_execz .LBB0_803
	v_cvt_pk_bf16_f32 v178, v178, v179
	v_cvt_pk_bf16_f32 v179, v186, v187
	v_cvt_pk_bf16_f32 v180, v176, v177
	v_cvt_pk_bf16_f32 v181, v188, v189
	global_store_dwordx4 v[182:183], v[178:181], off

.LBB0_805:
	s_or_b64 exec, exec, s[50:51]
	v_add_u32_e32 v176, 0x20010, v191
	ds_read_b128 v[176:179], v176
	s_waitcnt lgkmcnt(0)
	v_pk_add_f32 v[176:177], v[176:177], v[178:179]
	s_nop 0
	v_add_f32_e32 v176, v176, v177
	v_fmac_f32_e32 v190, 0x3c000000, v176
	v_rsq_f32_e32 v176, v190
	s_nop 0
	v_mul_f32_e32 v176, v244, v176
	v_pk_mul_f32 v[178:179], v[68:69], v[176:177] op_sel_hi:[1,0]
	v_pk_mul_f32 v[184:185], v[70:71], v[176:177] op_sel_hi:[1,0]
	v_pk_mul_f32 v[188:189], v[64:65], v[176:177] op_sel_hi:[1,0]
	v_pk_mul_f32 v[176:177], v[66:67], v[176:177] op_sel_hi:[1,0]
	v_pk_mul_f32 v[186:187], v[154:155], v[184:185]
	v_pk_mul_f32 v[178:179], v[152:153], v[178:179]
	v_pk_mul_f32 v[184:185], v[158:159], v[176:177]
	v_pk_mul_f32 v[176:177], v[156:157], v[188:189]
	s_and_saveexec_b64 s[50:51], vcc
	s_xor_b64 s[50:51], exec, s[50:51]
	s_cbranch_execz .LBB0_807
	v_cvt_pk_bf16_f32 v168, v178, v179
	v_cvt_pk_bf16_f32 v169, v186, v187
	v_cvt_pk_bf16_f32 v170, v176, v177
	v_cvt_pk_bf16_f32 v171, v184, v185
	global_store_dwordx4 v[182:183], v[168:171], off offset:256

.LBB0_809:
	s_or_b64 exec, exec, s[50:51]
	v_add_u32_e32 v172, 0x80, v240
	v_lshlrev_b32_e32 v183, 5, v172
	v_add_u32_e32 v168, 0x20000, v183
	ds_read_b128 v[168:171], v168
	v_fmamk_f32 v173, v246, 0x3a800000, v238
	v_mul_f32_e32 v182, 0x358637bd, v173
	v_add_u32_e32 v174, s41, v172
	s_waitcnt lgkmcnt(0)
	v_pk_add_f32 v[168:169], v[168:169], v[170:171]
	s_nop 0
	v_add_f32_e32 v168, v168, v169
	v_fmamk_f32 v168, v168, 0x3c000000, v182
	v_rsq_f32_e32 v170, v168
	v_mad_i64_i32 v[168:169], s[50:51], s60, v174, 0
	v_lshl_add_u64 v[176:177], v[168:169], 1, s[8:9]
	v_mul_f32_e32 v168, v244, v170
	v_pk_mul_f32 v[172:173], v[62:63], v[168:169] op_sel_hi:[1,0]
	v_pk_mul_f32 v[170:171], v[60:61], v[168:169] op_sel_hi:[1,0]
	v_pk_mul_f32 v[178:179], v[154:155], v[172:173]
	v_pk_mul_f32 v[172:173], v[56:57], v[168:169] op_sel_hi:[1,0]
	v_pk_mul_f32 v[168:169], v[58:59], v[168:169] op_sel_hi:[1,0]
	v_lshl_add_u64 v[174:175], v[222:223], 1, v[176:177]
	v_pk_mul_f32 v[170:171], v[152:153], v[170:171]
	v_pk_mul_f32 v[180:181], v[158:159], v[168:169]
	v_pk_mul_f32 v[168:169], v[156:157], v[172:173]
	s_and_saveexec_b64 s[50:51], vcc
	s_xor_b64 s[50:51], exec, s[50:51]
	s_cbranch_execz .LBB0_811
	v_cvt_pk_bf16_f32 v170, v170, v171
	v_cvt_pk_bf16_f32 v171, v178, v179
	v_cvt_pk_bf16_f32 v172, v168, v169
	v_cvt_pk_bf16_f32 v173, v180, v181
	global_store_dwordx4 v[174:175], v[170:173], off

.LBB0_813:
	s_or_b64 exec, exec, s[50:51]
	v_add_u32_e32 v168, 0x20010, v183
	ds_read_b128 v[168:171], v168
	s_waitcnt lgkmcnt(0)
	v_pk_add_f32 v[168:169], v[168:169], v[170:171]
	s_nop 0
	v_add_f32_e32 v168, v168, v169
	v_fmac_f32_e32 v182, 0x3c000000, v168
	v_rsq_f32_e32 v168, v182
	s_nop 0
	v_mul_f32_e32 v168, v244, v168
	v_pk_mul_f32 v[170:171], v[52:53], v[168:169] op_sel_hi:[1,0]
	v_pk_mul_f32 v[176:177], v[54:55], v[168:169] op_sel_hi:[1,0]
	v_pk_mul_f32 v[180:181], v[44:45], v[168:169] op_sel_hi:[1,0]
	v_pk_mul_f32 v[168:169], v[46:47], v[168:169] op_sel_hi:[1,0]
	v_pk_mul_f32 v[178:179], v[154:155], v[176:177]
	v_pk_mul_f32 v[170:171], v[152:153], v[170:171]
	v_pk_mul_f32 v[176:177], v[158:159], v[168:169]
	v_pk_mul_f32 v[168:169], v[156:157], v[180:181]
	s_and_saveexec_b64 s[50:51], vcc
	s_xor_b64 s[50:51], exec, s[50:51]
	s_cbranch_execz .LBB0_815
	v_cvt_pk_bf16_f32 v160, v170, v171
	v_cvt_pk_bf16_f32 v161, v178, v179
	v_cvt_pk_bf16_f32 v162, v168, v169
	v_cvt_pk_bf16_f32 v163, v176, v177
	global_store_dwordx4 v[174:175], v[160:163], off offset:256

.LBB0_817:
	s_or_b64 exec, exec, s[50:51]
	v_add_u32_e32 v164, 0x90, v240
	v_lshlrev_b32_e32 v175, 5, v164
	v_add_u32_e32 v160, 0x20000, v175
	ds_read_b128 v[160:163], v160
	v_fmamk_f32 v165, v245, 0x3a800000, v238
	v_mul_f32_e32 v174, 0x358637bd, v165
	v_add_u32_e32 v166, s41, v164
	s_waitcnt lgkmcnt(0)
	v_pk_add_f32 v[160:161], v[160:161], v[162:163]
	s_nop 0
	v_add_f32_e32 v160, v160, v161
	v_fmamk_f32 v160, v160, 0x3c000000, v174
	v_rsq_f32_e32 v162, v160
	v_mad_i64_i32 v[160:161], s[50:51], s60, v166, 0
	v_lshl_add_u64 v[168:169], v[160:161], 1, s[8:9]
	v_mul_f32_e32 v160, v244, v162
	v_pk_mul_f32 v[164:165], v[50:51], v[160:161] op_sel_hi:[1,0]
	v_pk_mul_f32 v[162:163], v[48:49], v[160:161] op_sel_hi:[1,0]
	v_pk_mul_f32 v[170:171], v[154:155], v[164:165]
	v_pk_mul_f32 v[164:165], v[40:41], v[160:161] op_sel_hi:[1,0]
	v_pk_mul_f32 v[160:161], v[42:43], v[160:161] op_sel_hi:[1,0]
	v_lshl_add_u64 v[166:167], v[222:223], 1, v[168:169]
	v_pk_mul_f32 v[162:163], v[152:153], v[162:163]
	v_pk_mul_f32 v[172:173], v[158:159], v[160:161]
	v_pk_mul_f32 v[160:161], v[156:157], v[164:165]
	s_and_saveexec_b64 s[50:51], vcc
	s_xor_b64 s[50:51], exec, s[50:51]
	s_cbranch_execz .LBB0_819
	v_cvt_pk_bf16_f32 v162, v162, v163
	v_cvt_pk_bf16_f32 v163, v170, v171
	v_cvt_pk_bf16_f32 v164, v160, v161
	v_cvt_pk_bf16_f32 v165, v172, v173
	global_store_dwordx4 v[166:167], v[162:165], off

.LBB0_821:
	s_or_b64 exec, exec, s[50:51]
	v_add_u32_e32 v160, 0x20010, v175
	ds_read_b128 v[160:163], v160
	s_waitcnt lgkmcnt(0)
	v_pk_add_f32 v[160:161], v[160:161], v[162:163]
	s_nop 0
	v_add_f32_e32 v160, v160, v161
	v_fmac_f32_e32 v174, 0x3c000000, v160
	v_rsq_f32_e32 v160, v174
	s_nop 0
	v_mul_f32_e32 v160, v244, v160
	v_pk_mul_f32 v[162:163], v[36:37], v[160:161] op_sel_hi:[1,0]
	v_pk_mul_f32 v[168:169], v[38:39], v[160:161] op_sel_hi:[1,0]
	v_pk_mul_f32 v[172:173], v[28:29], v[160:161] op_sel_hi:[1,0]
	v_pk_mul_f32 v[160:161], v[30:31], v[160:161] op_sel_hi:[1,0]
	v_pk_mul_f32 v[170:171], v[154:155], v[168:169]
	v_pk_mul_f32 v[162:163], v[152:153], v[162:163]
	v_pk_mul_f32 v[168:169], v[158:159], v[160:161]
	v_pk_mul_f32 v[160:161], v[156:157], v[172:173]
	s_and_saveexec_b64 s[50:51], vcc
	s_xor_b64 s[50:51], exec, s[50:51]
	s_cbranch_execz .LBB0_823
	v_cvt_pk_bf16_f32 v144, v162, v163
	v_cvt_pk_bf16_f32 v145, v170, v171
	v_cvt_pk_bf16_f32 v146, v160, v161
	v_cvt_pk_bf16_f32 v147, v168, v169
	global_store_dwordx4 v[166:167], v[144:147], off offset:256

.LBB0_825:
	s_or_b64 exec, exec, s[50:51]
	v_add_u32_e32 v148, 0xa0, v240
	v_lshlrev_b32_e32 v167, 5, v148
	v_add_u32_e32 v144, 0x20000, v167
	ds_read_b128 v[144:147], v144
	v_fmamk_f32 v149, v241, 0x3a800000, v238
	v_mul_f32_e32 v166, 0x358637bd, v149
	v_add_u32_e32 v150, s41, v148
	s_waitcnt lgkmcnt(0)
	v_pk_add_f32 v[144:145], v[144:145], v[146:147]
	s_nop 0
	v_add_f32_e32 v144, v144, v145
	v_fmamk_f32 v144, v144, 0x3c000000, v166
	v_rsq_f32_e32 v146, v144
	v_mad_i64_i32 v[144:145], s[50:51], s60, v150, 0
	v_lshl_add_u64 v[160:161], v[144:145], 1, s[8:9]
	v_mul_f32_e32 v144, v244, v146
	v_pk_mul_f32 v[148:149], v[34:35], v[144:145] op_sel_hi:[1,0]
	v_pk_mul_f32 v[146:147], v[32:33], v[144:145] op_sel_hi:[1,0]
	v_pk_mul_f32 v[162:163], v[154:155], v[148:149]
	v_pk_mul_f32 v[148:149], v[24:25], v[144:145] op_sel_hi:[1,0]
	v_pk_mul_f32 v[144:145], v[26:27], v[144:145] op_sel_hi:[1,0]
	v_lshl_add_u64 v[150:151], v[222:223], 1, v[160:161]
	v_pk_mul_f32 v[146:147], v[152:153], v[146:147]
	v_pk_mul_f32 v[164:165], v[158:159], v[144:145]
	v_pk_mul_f32 v[144:145], v[156:157], v[148:149]
	s_and_saveexec_b64 s[50:51], vcc
	s_xor_b64 s[50:51], exec, s[50:51]
	s_cbranch_execz .LBB0_827
	v_cvt_pk_bf16_f32 v146, v146, v147
	v_cvt_pk_bf16_f32 v147, v162, v163
	v_cvt_pk_bf16_f32 v148, v144, v145
	v_cvt_pk_bf16_f32 v149, v164, v165
	global_store_dwordx4 v[150:151], v[146:149], off

.LBB0_829:
	s_or_b64 exec, exec, s[50:51]
	v_add_u32_e32 v144, 0x20010, v167
	ds_read_b128 v[144:147], v144
	s_waitcnt lgkmcnt(0)
	v_pk_add_f32 v[144:145], v[144:145], v[146:147]
	s_nop 0
	v_add_f32_e32 v144, v144, v145
	v_fmac_f32_e32 v166, 0x3c000000, v144
	v_rsq_f32_e32 v144, v166
	s_nop 0
	v_mul_f32_e32 v144, v244, v144
	v_pk_mul_f32 v[146:147], v[20:21], v[144:145] op_sel_hi:[1,0]
	v_pk_mul_f32 v[160:161], v[22:23], v[144:145] op_sel_hi:[1,0]
	v_pk_mul_f32 v[164:165], v[12:13], v[144:145] op_sel_hi:[1,0]
	v_pk_mul_f32 v[144:145], v[14:15], v[144:145] op_sel_hi:[1,0]
	v_pk_mul_f32 v[162:163], v[154:155], v[160:161]
	v_pk_mul_f32 v[146:147], v[152:153], v[146:147]
	v_pk_mul_f32 v[160:161], v[158:159], v[144:145]
	v_pk_mul_f32 v[144:145], v[156:157], v[164:165]
	s_and_saveexec_b64 s[50:51], vcc
	s_xor_b64 s[50:51], exec, s[50:51]
	s_cbranch_execz .LBB0_831
	v_cvt_pk_bf16_f32 v136, v146, v147
	v_cvt_pk_bf16_f32 v137, v162, v163
	v_cvt_pk_bf16_f32 v138, v144, v145
	v_cvt_pk_bf16_f32 v139, v160, v161
	global_store_dwordx4 v[150:151], v[136:139], off offset:256

.LBB0_833:
	s_or_b64 exec, exec, s[50:51]
	v_add_u32_e32 v140, 0xb0, v240
	v_lshlrev_b32_e32 v151, 5, v140
	v_add_u32_e32 v136, 0x20000, v151
	ds_read_b128 v[136:139], v136
	v_fmamk_f32 v141, v219, 0x3a800000, v238
	v_mul_f32_e32 v150, 0x358637bd, v141
	v_add_u32_e32 v142, s41, v140
	s_waitcnt lgkmcnt(0)
	v_pk_add_f32 v[136:137], v[136:137], v[138:139]
	s_nop 0
	v_add_f32_e32 v136, v136, v137
	v_fmamk_f32 v136, v136, 0x3c000000, v150
	v_rsq_f32_e32 v138, v136
	v_mad_i64_i32 v[136:137], s[50:51], s60, v142, 0
	v_lshl_add_u64 v[144:145], v[136:137], 1, s[8:9]
	v_mul_f32_e32 v136, v244, v138
	v_pk_mul_f32 v[140:141], v[18:19], v[136:137] op_sel_hi:[1,0]
	v_pk_mul_f32 v[138:139], v[16:17], v[136:137] op_sel_hi:[1,0]
	v_pk_mul_f32 v[146:147], v[154:155], v[140:141]
	v_pk_mul_f32 v[140:141], v[8:9], v[136:137] op_sel_hi:[1,0]
	v_pk_mul_f32 v[136:137], v[10:11], v[136:137] op_sel_hi:[1,0]
	v_lshl_add_u64 v[142:143], v[222:223], 1, v[144:145]
	v_pk_mul_f32 v[138:139], v[152:153], v[138:139]
	v_pk_mul_f32 v[148:149], v[158:159], v[136:137]
	v_pk_mul_f32 v[136:137], v[156:157], v[140:141]
	s_and_saveexec_b64 s[8:9], vcc
	s_xor_b64 s[8:9], exec, s[8:9]
	s_cbranch_execz .LBB0_835
	v_cvt_pk_bf16_f32 v138, v138, v139
	v_cvt_pk_bf16_f32 v139, v146, v147
	v_cvt_pk_bf16_f32 v140, v136, v137
	v_cvt_pk_bf16_f32 v141, v148, v149
	global_store_dwordx4 v[142:143], v[138:141], off

.LBB0_837:
	s_or_b64 exec, exec, s[8:9]
	v_add_u32_e32 v136, 0x20010, v151
	ds_read_b128 v[136:139], v136
	s_waitcnt lgkmcnt(0)
	v_pk_add_f32 v[136:137], v[136:137], v[138:139]
	s_nop 0
	v_add_f32_e32 v136, v136, v137
	v_fmac_f32_e32 v150, 0x3c000000, v136
	v_rsq_f32_e32 v136, v150
	s_nop 0
	v_mul_f32_e32 v136, v244, v136
	v_pk_mul_f32 v[138:139], v[4:5], v[136:137] op_sel_hi:[1,0]
	v_pk_mul_f32 v[144:145], v[6:7], v[136:137] op_sel_hi:[1,0]
	v_pk_mul_f32 v[148:149], v[0:1], v[136:137] op_sel_hi:[1,0]
	v_pk_mul_f32 v[136:137], v[2:3], v[136:137] op_sel_hi:[1,0]
	v_pk_mul_f32 v[146:147], v[154:155], v[144:145]
	v_pk_mul_f32 v[138:139], v[152:153], v[138:139]
	v_pk_mul_f32 v[144:145], v[158:159], v[136:137]
	v_pk_mul_f32 v[136:137], v[156:157], v[148:149]
	s_and_saveexec_b64 s[8:9], vcc
	s_xor_b64 s[8:9], exec, s[8:9]
	s_cbranch_execz .LBB0_839
	v_cvt_pk_bf16_f32 v128, v138, v139
	v_cvt_pk_bf16_f32 v129, v146, v147
	v_cvt_pk_bf16_f32 v130, v136, v137
	v_cvt_pk_bf16_f32 v131, v144, v145
	global_store_dwordx4 v[142:143], v[128:131], off offset:256
